# RK_G2 W2 epilogue: removed leftover store-throttling vmcnt waits at block starts (loads were hoisted earlier)
# baseline (speedup 1.0000x reference)
; #define PIN(i) (gl_in(p.in[lnd(i)]))
; #define PW(T, off) ((T*)(lndp(p.ws) + (off)))
; template <int EPI>
; DEVI void gemm_epi(const Params& p, const GJob& jb, f32x16 (&acc)[2][2], int rbase, int cbase, int lane) {
;   const float* i_rk_w0 = PIN(23);
;   const float* i_rk_a0 = PIN(26);
;   char* ar = PW(char, W_arena);
; #pragma unroll
;   for (int i = 0; i < 2; ++i) {
; #pragma unroll
;     for (int r = 0; r < 16; ++r) {
;       const int row = rbase + i * 32 + accrow(r, lane);
;       if (row < M) {
; #pragma unroll
;         for (int j = 0; j < 2; ++j) {
;           const int col = cbase + j * 32 + (lane & 31);
;           const float v = acc[i][j][r];
;           if (EPI == EPI_SSD_IN) {
;             if (col < 2048) ((bf16*)(ar + S_ZB))[(size_t)row * 2048 + col] = f2bf(v);
;             else if (col < 6144) ((bf16*)(ar + S_XBC))[(size_t)row * 4096 + col - 2048] = f2bf(v);
;             else if (col < 6176) ((float*)(ar + S_DTRAW))[(size_t)row * 32 + col - 6144] = v;
;           } else if (EPI == EPI_RESID) {
;             PW(bf16, W_Z)[(size_t)row * 1024 + col] = f2bf(ALPHA * bf2f(PW(bf16, W_Xb)[(size_t)row * 1024 + col]) + v);
;           } else if (EPI == EPI_GU) {
;             ((bf16*)(ar + F_GU))[(size_t)row * 5632 + col] = f2bf(v);
;           } else if (EPI == EPI_BF16) {
;             ((bf16*)jb.of)[(size_t)row * 1024 + col] = f2bf(v);
;           } else if (EPI == EPI_F32) {
;             jb.of[(size_t)row * 1024 + col] = v;
;           } else if (EPI == EPI_RK_W1) {
;             if (col < 64) ((bf16*)(ar + R_HW))[(size_t)row * 64 + col] = f2bf(tanhfast(v));
;           } else if (EPI == EPI_RK_A1) {
;             if (col < 64) ((bf16*)(ar + R_HA))[(size_t)row * 64 + col] = f2bf(v);
;           } else if (EPI == EPI_RK_G1) {
;             if (col < 192) ((bf16*)(ar + R_HG))[(size_t)row * 192 + col] = f2bf(col < 160 ? sigmf(v) : 0.f);
;           } else if (EPI == EPI_RK_W2) {
;             const float z = i_rk_w0[col] + v;
;             const float wl = -softplusf(-z) - 0.5f;
;             ((float*)(ar + R_W))[(size_t)row * 1024 + col] = __expf(-__expf(wl));
;           } else if (EPI == EPI_RESID_TAIL) {
;             atomicAdd(PW(float, W_ZT) + (size_t)(row - 16384) * 1024 + col, v);
;           } else if (EPI == EPI_RK_A2) {
;             ((bf16*)(ar + R_A))[(size_t)row * 1024 + col] = f2bf(sigmf(i_rk_a0[col] + v));
.LBB0_510:
	s_andn2_b64 vcc, exec, s[4:5]
	s_cbranch_vccnz .LBB0_356
	v_lshrrev_b32_e32 v70, 3, v70
	v_or_b32_e32 v64, v69, v96
	s_mov_b64 s[2:3], -1
	s_cmp_lg_u32 s25, 9
	v_and_b32_e32 v69, 4, v70
	v_ashrrev_i32_e32 v65, 31, v64
	s_cbranch_scc0 .LBB0_577
	s_mov_b32 s2, 23
	s_ashr_i32 s3, s2, 31
	s_lshl_b64 s[2:3], s[2:3], 3
	s_add_u32 s2, s0, s2
	s_addc_u32 s3, s1, s3
	s_load_dwordx2 s[8:9], s[2:3], 0x0
	s_mov_b32 s2, 26
	s_waitcnt lgkmcnt(0)
	s_ashr_i32 s3, s2, 31
	s_lshl_b64 s[2:3], s[2:3], 3
	s_add_u32 s2, s0, s2
	s_addc_u32 s3, s1, s3
	s_load_dwordx2 s[2:3], s[2:3], 0x0
	s_mov_b64 s[4:5], s[74:75]
	v_or_b32_e32 v66, v68, v69
	s_waitcnt lgkmcnt(0)
	s_add_u32 s6, s4, 0x11d7c000
	s_addc_u32 s7, s5, 0
	v_cmp_gt_i32_e32 vcc, s90, v66
	v_lshlrev_b64 v[172:173], 2, v[64:65]
	v_lshl_add_u64 v[172:173], v[172:173], 0, s[8:9]
	global_load_dword v170, v[172:173], off
	global_load_dword v171, v[172:173], off offset:128
	s_waitcnt vmcnt(0)
	s_and_saveexec_b64 s[2:3], vcc
	s_cbranch_execz .LBB0_514
	v_lshlrev_b64 v[72:73], 2, v[64:65]
	v_lshl_add_u64 v[74:75], s[8:9], 0, v[72:73]
	v_mov_b32_e32 v67, v170
	s_mov_b32 s5, 0x3f317217
	s_mov_b32 s18, 0x7f800000
	s_mov_b32 s4, 0xc1a00000
	v_add_f32_e32 v67, v32, v67
	v_mul_f32_e32 v71, 0xbfb8aa3b, v67
	v_exp_f32_e32 v71, v71
	s_nop 0
	v_add_f32_e32 v71, 1.0, v71
	v_cmp_gt_f32_e32 vcc, s69, v71
	s_nop 1
	v_cndmask_b32_e64 v76, 0, 32, vcc
	v_ldexp_f32 v71, v71, v76
	v_log_f32_e32 v71, v71
	v_cndmask_b32_e32 v76, 0, v216, vcc
	v_mul_f32_e32 v77, 0x3f317217, v71
	v_fma_f32 v77, v71, s5, -v77
	v_fmac_f32_e32 v77, 0x3377d1cf, v71
	v_fmac_f32_e32 v77, 0x3f317217, v71
	v_cmp_lt_f32_e64 vcc, |v71|, s18
	s_nop 1
	v_cndmask_b32_e32 v71, v71, v77, vcc
	v_sub_f32_e32 v71, v71, v76
	v_cmp_gt_f32_e32 vcc, s4, v67
	s_nop 1
	v_cndmask_b32_e64 v67, v71, -v67, vcc
	v_sub_f32_e32 v67, -0.5, v67
	v_mul_f32_e32 v67, 0x3fb8aa3b, v67
	v_exp_f32_e32 v71, v67
	v_ashrrev_i32_e32 v67, 31, v66
	v_lshlrev_b64 v[66:67], 12, v[66:67]
	v_lshl_add_u64 v[66:67], s[6:7], 0, v[66:67]
	v_mul_f32_e32 v71, 0xbfb8aa3b, v71
	v_exp_f32_e32 v71, v71
	v_lshl_add_u64 v[66:67], v[66:67], 0, v[72:73]
	global_store_dword v[66:67], v71, off
	v_mov_b32_e32 v71, v171
	v_add_f32_e32 v71, v48, v71
	v_mul_f32_e32 v72, 0xbfb8aa3b, v71
	v_exp_f32_e32 v72, v72
	s_nop 0
	v_add_f32_e32 v72, 1.0, v72
	v_cmp_gt_f32_e32 vcc, s69, v72
	s_nop 1
	v_cndmask_b32_e64 v73, 0, 32, vcc
	v_ldexp_f32 v72, v72, v73
	v_log_f32_e32 v72, v72
	v_cndmask_b32_e32 v73, 0, v216, vcc
	v_mul_f32_e32 v74, 0x3f317217, v72
	v_fma_f32 v74, v72, s5, -v74
	v_fmac_f32_e32 v74, 0x3377d1cf, v72
	v_fmac_f32_e32 v74, 0x3f317217, v72
	v_cmp_lt_f32_e64 vcc, |v72|, s18
	s_nop 1
	v_cndmask_b32_e32 v72, v72, v74, vcc
	v_sub_f32_e32 v72, v72, v73
	v_cmp_gt_f32_e32 vcc, s4, v71
	s_nop 1
	v_cndmask_b32_e64 v71, v72, -v71, vcc
	v_sub_f32_e32 v71, -0.5, v71
	v_mul_f32_e32 v71, 0x3fb8aa3b, v71
	v_exp_f32_e32 v71, v71
	s_nop 0
	v_mul_f32_e32 v71, 0xbfb8aa3b, v71
	v_exp_f32_e32 v71, v71
	global_store_dword v[66:67], v71, off offset:128
.LBB0_514:
	s_or_b64 exec, exec, s[2:3]
	v_or_b32_e32 v71, 1, v69
	v_or_b32_e32 v66, v71, v68
	v_cmp_gt_i32_e32 vcc, s90, v66
	s_and_saveexec_b64 s[2:3], vcc
	s_cbranch_execz .LBB0_516
	v_lshlrev_b64 v[72:73], 2, v[64:65]
	v_lshl_add_u64 v[74:75], s[8:9], 0, v[72:73]
	v_mov_b32_e32 v67, v170
	s_mov_b32 s5, 0x3f317217
	s_mov_b32 s18, 0x7f800000
	s_mov_b32 s4, 0xc1a00000
	v_add_f32_e32 v67, v33, v67
	v_mul_f32_e32 v76, 0xbfb8aa3b, v67
	v_exp_f32_e32 v76, v76
	s_nop 0
	v_add_f32_e32 v76, 1.0, v76
	v_cmp_gt_f32_e32 vcc, s69, v76
	s_nop 1
	v_cndmask_b32_e64 v77, 0, 32, vcc
	v_ldexp_f32 v76, v76, v77
	v_log_f32_e32 v76, v76
	v_cndmask_b32_e32 v77, 0, v216, vcc
	v_mul_f32_e32 v78, 0x3f317217, v76
	v_fma_f32 v78, v76, s5, -v78
	v_fmac_f32_e32 v78, 0x3377d1cf, v76
	v_fmac_f32_e32 v78, 0x3f317217, v76
	v_cmp_lt_f32_e64 vcc, |v76|, s18
	s_nop 1
	v_cndmask_b32_e32 v76, v76, v78, vcc
	v_sub_f32_e32 v76, v76, v77
	v_cmp_gt_f32_e32 vcc, s4, v67
	s_nop 1
	v_cndmask_b32_e64 v67, v76, -v67, vcc
	v_sub_f32_e32 v67, -0.5, v67
	v_mul_f32_e32 v67, 0x3fb8aa3b, v67
	v_exp_f32_e32 v76, v67
	v_ashrrev_i32_e32 v67, 31, v66
	v_lshlrev_b64 v[66:67], 12, v[66:67]
	v_lshl_add_u64 v[66:67], s[6:7], 0, v[66:67]
	v_mul_f32_e32 v76, 0xbfb8aa3b, v76
	v_exp_f32_e32 v76, v76
	v_lshl_add_u64 v[66:67], v[66:67], 0, v[72:73]
	global_store_dword v[66:67], v76, off
	v_mov_b32_e32 v72, v171
	v_add_f32_e32 v72, v49, v72
	v_mul_f32_e32 v73, 0xbfb8aa3b, v72
	v_exp_f32_e32 v73, v73
	s_nop 0
	v_add_f32_e32 v73, 1.0, v73
	v_cmp_gt_f32_e32 vcc, s69, v73
	s_nop 1
	v_cndmask_b32_e64 v74, 0, 32, vcc
	v_ldexp_f32 v73, v73, v74
	v_log_f32_e32 v73, v73
	v_cndmask_b32_e32 v74, 0, v216, vcc
	v_mul_f32_e32 v75, 0x3f317217, v73
	v_fma_f32 v75, v73, s5, -v75
	v_fmac_f32_e32 v75, 0x3377d1cf, v73
	v_fmac_f32_e32 v75, 0x3f317217, v73
	v_cmp_lt_f32_e64 vcc, |v73|, s18
	s_nop 1
	v_cndmask_b32_e32 v73, v73, v75, vcc
	v_sub_f32_e32 v73, v73, v74
	v_cmp_gt_f32_e32 vcc, s4, v72
	s_nop 1
	v_cndmask_b32_e64 v72, v73, -v72, vcc
	v_sub_f32_e32 v72, -0.5, v72
	v_mul_f32_e32 v72, 0x3fb8aa3b, v72
	v_exp_f32_e32 v72, v72
	s_nop 0
	v_mul_f32_e32 v72, 0xbfb8aa3b, v72
	v_exp_f32_e32 v72, v72
	global_store_dword v[66:67], v72, off offset:128

; #define PW(T, off) ((T*)(lndp(p.ws) + (off)))
; DEVI float bf2f(bf16 h) { return __uint_as_float(((unsigned)h) << 16); }
; DEVI float sigmf(float x) { return __builtin_amdgcn_rcpf(1.f + __expf(-x)); }
; DEVI float softplusf(float x) { return x > 20.f ? x : __logf(1.f + __expf(x)); }
; DEVI float tanhfast(float x) { return 1.f - 2.f / (__expf(2.f * x) + 1.f); }
; DEVI int accrow(int r, int lane) { return (r & 3) + 8 * (r >> 2) + 4 * (lane >> 5); }
; template <int EPI>
; DEVI void gemm_epi(const Params& p, const GJob& jb, f32x16 (&acc)[2][2], int rbase, int cbase, int lane) {
;     ...
;       const int row = rbase + i * 32 + accrow(r, lane);
;       if (row < M) {
; #pragma unroll
;         for (int j = 0; j < 2; ++j) {
;           const int col = cbase + j * 32 + (lane & 31);
;           const float v = acc[i][j][r];
;           if (EPI == EPI_SSD_IN) {
;             if (col < 2048) ((bf16*)(ar + S_ZB))[(size_t)row * 2048 + col] = f2bf(v);
;             else if (col < 6144) ((bf16*)(ar + S_XBC))[(size_t)row * 4096 + col - 2048] = f2bf(v);
;             else if (col < 6176) ((float*)(ar + S_DTRAW))[(size_t)row * 32 + col - 6144] = v;
;           } else if (EPI == EPI_RESID) {
;             PW(bf16, W_Z)[(size_t)row * 1024 + col] = f2bf(ALPHA * bf2f(PW(bf16, W_Xb)[(size_t)row * 1024 + col]) + v);
;           } else if (EPI == EPI_GU) {
;             ((bf16*)(ar + F_GU))[(size_t)row * 5632 + col] = f2bf(v);
;           } else if (EPI == EPI_BF16) {
;             ((bf16*)jb.of)[(size_t)row * 1024 + col] = f2bf(v);
;           } else if (EPI == EPI_F32) {
;             jb.of[(size_t)row * 1024 + col] = v;
;           } else if (EPI == EPI_RK_W1) {
;             if (col < 64) ((bf16*)(ar + R_HW))[(size_t)row * 64 + col] = f2bf(tanhfast(v));
;           } else if (EPI == EPI_RK_A1) {
;             if (col < 64) ((bf16*)(ar + R_HA))[(size_t)row * 64 + col] = f2bf(v);
;           } else if (EPI == EPI_RK_G1) {
;             if (col < 192) ((bf16*)(ar + R_HG))[(size_t)row * 192 + col] = f2bf(col < 160 ? sigmf(v) : 0.f);
;           } else if (EPI == EPI_RK_W2) {
;             const float z = i_rk_w0[col] + v;
;             const float wl = -softplusf(-z) - 0.5f;
;             ((float*)(ar + R_W))[(size_t)row * 1024 + col] = __expf(-__expf(wl));
.LBB0_524:
	s_or_b64 exec, exec, s[2:3]
	v_or_b32_e32 v76, 10, v69
	v_or_b32_e32 v66, v76, v68
	v_cmp_gt_i32_e32 vcc, s90, v66
	s_and_saveexec_b64 s[2:3], vcc
	s_cbranch_execz .LBB0_526
	v_lshlrev_b64 v[78:79], 2, v[64:65]
	v_lshl_add_u64 v[80:81], s[8:9], 0, v[78:79]
	v_mov_b32_e32 v67, v170
	s_mov_b32 s5, 0x3f317217
	s_mov_b32 s18, 0x7f800000
	s_mov_b32 s4, 0xc1a00000
	v_add_f32_e32 v67, v38, v67
	v_mul_f32_e32 v77, 0xbfb8aa3b, v67
	v_exp_f32_e32 v77, v77
	s_nop 0
	v_add_f32_e32 v77, 1.0, v77
	v_cmp_gt_f32_e32 vcc, s69, v77
	s_nop 1
	v_cndmask_b32_e64 v82, 0, 32, vcc
	v_ldexp_f32 v77, v77, v82
	v_log_f32_e32 v77, v77
	v_cndmask_b32_e32 v82, 0, v216, vcc
	v_mul_f32_e32 v83, 0x3f317217, v77
	v_fma_f32 v83, v77, s5, -v83
	v_fmac_f32_e32 v83, 0x3377d1cf, v77
	v_fmac_f32_e32 v83, 0x3f317217, v77
	v_cmp_lt_f32_e64 vcc, |v77|, s18
	s_nop 1
	v_cndmask_b32_e32 v77, v77, v83, vcc
	v_sub_f32_e32 v77, v77, v82
	v_cmp_gt_f32_e32 vcc, s4, v67
	s_nop 1
	v_cndmask_b32_e64 v67, v77, -v67, vcc
	v_sub_f32_e32 v67, -0.5, v67
	v_mul_f32_e32 v67, 0x3fb8aa3b, v67
	v_exp_f32_e32 v77, v67
	v_ashrrev_i32_e32 v67, 31, v66
	v_lshlrev_b64 v[66:67], 12, v[66:67]
	v_lshl_add_u64 v[66:67], s[6:7], 0, v[66:67]
	v_mul_f32_e32 v77, 0xbfb8aa3b, v77
	v_exp_f32_e32 v77, v77
	v_lshl_add_u64 v[66:67], v[66:67], 0, v[78:79]
	global_store_dword v[66:67], v77, off
	v_mov_b32_e32 v77, v171
	v_add_f32_e32 v77, v54, v77
	v_mul_f32_e32 v78, 0xbfb8aa3b, v77
	v_exp_f32_e32 v78, v78
	s_nop 0
	v_add_f32_e32 v78, 1.0, v78
	v_cmp_gt_f32_e32 vcc, s69, v78
	s_nop 1
	v_cndmask_b32_e64 v79, 0, 32, vcc
	v_ldexp_f32 v78, v78, v79
	v_log_f32_e32 v78, v78
	v_cndmask_b32_e32 v79, 0, v216, vcc
	v_mul_f32_e32 v80, 0x3f317217, v78
	v_fma_f32 v80, v78, s5, -v80
	v_fmac_f32_e32 v80, 0x3377d1cf, v78
	v_fmac_f32_e32 v80, 0x3f317217, v78
	v_cmp_lt_f32_e64 vcc, |v78|, s18
	s_nop 1
	v_cndmask_b32_e32 v78, v78, v80, vcc
	v_sub_f32_e32 v78, v78, v79
	v_cmp_gt_f32_e32 vcc, s4, v77
	s_nop 1
	v_cndmask_b32_e64 v77, v78, -v77, vcc
	v_sub_f32_e32 v77, -0.5, v77
	v_mul_f32_e32 v77, 0x3fb8aa3b, v77
	v_exp_f32_e32 v77, v77
	s_nop 0
	v_mul_f32_e32 v77, 0xbfb8aa3b, v77
	v_exp_f32_e32 v77, v77
	global_store_dword v[66:67], v77, off offset:128
.LBB0_526:
	s_or_b64 exec, exec, s[2:3]
	v_or_b32_e32 v77, 11, v70
	v_or_b32_e32 v66, v68, v77
	v_cmp_gt_i32_e32 vcc, s90, v66
	s_and_saveexec_b64 s[2:3], vcc
	s_cbranch_execz .LBB0_528
	v_lshlrev_b64 v[78:79], 2, v[64:65]
	v_lshl_add_u64 v[80:81], s[8:9], 0, v[78:79]
	v_mov_b32_e32 v67, v170
	s_mov_b32 s5, 0x3f317217
	s_mov_b32 s18, 0x7f800000
	s_mov_b32 s4, 0xc1a00000
	v_add_f32_e32 v67, v39, v67
	v_mul_f32_e32 v82, 0xbfb8aa3b, v67
	v_exp_f32_e32 v82, v82
	s_nop 0
	v_add_f32_e32 v82, 1.0, v82
	v_cmp_gt_f32_e32 vcc, s69, v82
	s_nop 1
	v_cndmask_b32_e64 v83, 0, 32, vcc
	v_ldexp_f32 v82, v82, v83
	v_log_f32_e32 v82, v82
	v_cndmask_b32_e32 v83, 0, v216, vcc
	v_mul_f32_e32 v84, 0x3f317217, v82
	v_fma_f32 v84, v82, s5, -v84
	v_fmac_f32_e32 v84, 0x3377d1cf, v82
	v_fmac_f32_e32 v84, 0x3f317217, v82
	v_cmp_lt_f32_e64 vcc, |v82|, s18
	s_nop 1
	v_cndmask_b32_e32 v82, v82, v84, vcc
	v_sub_f32_e32 v82, v82, v83
	v_cmp_gt_f32_e32 vcc, s4, v67
	s_nop 1
	v_cndmask_b32_e64 v67, v82, -v67, vcc
	v_sub_f32_e32 v67, -0.5, v67
	v_mul_f32_e32 v67, 0x3fb8aa3b, v67
	v_exp_f32_e32 v82, v67
	v_ashrrev_i32_e32 v67, 31, v66
	v_lshlrev_b64 v[66:67], 12, v[66:67]
	v_lshl_add_u64 v[66:67], s[6:7], 0, v[66:67]
	v_mul_f32_e32 v82, 0xbfb8aa3b, v82
	v_exp_f32_e32 v82, v82
	v_lshl_add_u64 v[66:67], v[66:67], 0, v[78:79]
	global_store_dword v[66:67], v82, off
	v_mov_b32_e32 v78, v171
	v_add_f32_e32 v78, v55, v78
	v_mul_f32_e32 v79, 0xbfb8aa3b, v78
	v_exp_f32_e32 v79, v79
	s_nop 0
	v_add_f32_e32 v79, 1.0, v79
	v_cmp_gt_f32_e32 vcc, s69, v79
	s_nop 1
	v_cndmask_b32_e64 v80, 0, 32, vcc
	v_ldexp_f32 v79, v79, v80
	v_log_f32_e32 v79, v79
	v_cndmask_b32_e32 v80, 0, v216, vcc
	v_mul_f32_e32 v81, 0x3f317217, v79
	v_fma_f32 v81, v79, s5, -v81
	v_fmac_f32_e32 v81, 0x3377d1cf, v79
	v_fmac_f32_e32 v81, 0x3f317217, v79
	v_cmp_lt_f32_e64 vcc, |v79|, s18
	s_nop 1
	v_cndmask_b32_e32 v79, v79, v81, vcc
	v_sub_f32_e32 v79, v79, v80
	v_cmp_gt_f32_e32 vcc, s4, v78
	s_nop 1
	v_cndmask_b32_e64 v78, v79, -v78, vcc
	v_sub_f32_e32 v78, -0.5, v78
	v_mul_f32_e32 v78, 0x3fb8aa3b, v78
	v_exp_f32_e32 v78, v78
	s_nop 0
	v_mul_f32_e32 v78, 0xbfb8aa3b, v78
	v_exp_f32_e32 v78, v78
	global_store_dword v[66:67], v78, off offset:128
.LBB0_528:
	s_or_b64 exec, exec, s[2:3]
	v_or_b32_e32 v78, 16, v69
	v_or_b32_e32 v66, v78, v68
	v_cmp_gt_i32_e32 vcc, s90, v66
	s_and_saveexec_b64 s[2:3], vcc
	s_cbranch_execz .LBB0_530
	v_lshlrev_b64 v[80:81], 2, v[64:65]
	v_lshl_add_u64 v[82:83], s[8:9], 0, v[80:81]
	v_mov_b32_e32 v67, v170
	s_mov_b32 s5, 0x3f317217
	s_mov_b32 s18, 0x7f800000
	s_mov_b32 s4, 0xc1a00000
	v_add_f32_e32 v67, v40, v67
	v_mul_f32_e32 v79, 0xbfb8aa3b, v67
	v_exp_f32_e32 v79, v79
	s_nop 0
	v_add_f32_e32 v79, 1.0, v79
	v_cmp_gt_f32_e32 vcc, s69, v79
	s_nop 1
	v_cndmask_b32_e64 v84, 0, 32, vcc
	v_ldexp_f32 v79, v79, v84
	v_log_f32_e32 v79, v79
	v_cndmask_b32_e32 v84, 0, v216, vcc
	v_mul_f32_e32 v85, 0x3f317217, v79
	v_fma_f32 v85, v79, s5, -v85
	v_fmac_f32_e32 v85, 0x3377d1cf, v79
	v_fmac_f32_e32 v85, 0x3f317217, v79
	v_cmp_lt_f32_e64 vcc, |v79|, s18
	s_nop 1
	v_cndmask_b32_e32 v79, v79, v85, vcc
	v_sub_f32_e32 v79, v79, v84
	v_cmp_gt_f32_e32 vcc, s4, v67
	s_nop 1
	v_cndmask_b32_e64 v67, v79, -v67, vcc
	v_sub_f32_e32 v67, -0.5, v67
	v_mul_f32_e32 v67, 0x3fb8aa3b, v67
	v_exp_f32_e32 v79, v67
	v_ashrrev_i32_e32 v67, 31, v66
	v_lshlrev_b64 v[66:67], 12, v[66:67]
	v_lshl_add_u64 v[66:67], s[6:7], 0, v[66:67]
	v_mul_f32_e32 v79, 0xbfb8aa3b, v79
	v_exp_f32_e32 v79, v79
	v_lshl_add_u64 v[66:67], v[66:67], 0, v[80:81]
	global_store_dword v[66:67], v79, off
	v_mov_b32_e32 v79, v171
	v_add_f32_e32 v79, v56, v79
	v_mul_f32_e32 v80, 0xbfb8aa3b, v79
	v_exp_f32_e32 v80, v80
	s_nop 0
	v_add_f32_e32 v80, 1.0, v80
	v_cmp_gt_f32_e32 vcc, s69, v80
	s_nop 1
	v_cndmask_b32_e64 v81, 0, 32, vcc
	v_ldexp_f32 v80, v80, v81
	v_log_f32_e32 v80, v80
	v_cndmask_b32_e32 v81, 0, v216, vcc
	v_mul_f32_e32 v82, 0x3f317217, v80
	v_fma_f32 v82, v80, s5, -v82
	v_fmac_f32_e32 v82, 0x3377d1cf, v80
	v_fmac_f32_e32 v82, 0x3f317217, v80
	v_cmp_lt_f32_e64 vcc, |v80|, s18
	s_nop 1
	v_cndmask_b32_e32 v80, v80, v82, vcc
	v_sub_f32_e32 v80, v80, v81
	v_cmp_gt_f32_e32 vcc, s4, v79
	s_nop 1
	v_cndmask_b32_e64 v79, v80, -v79, vcc
	v_sub_f32_e32 v79, -0.5, v79
	v_mul_f32_e32 v79, 0x3fb8aa3b, v79
	v_exp_f32_e32 v79, v79
	s_nop 0
	v_mul_f32_e32 v79, 0xbfb8aa3b, v79
	v_exp_f32_e32 v79, v79
	global_store_dword v[66:67], v79, off offset:128
; #define PW(T, off) ((T*)(lndp(p.ws) + (off)))
; DEVI float bf2f(bf16 h) { return __uint_as_float(((unsigned)h) << 16); }
; DEVI float sigmf(float x) { return __builtin_amdgcn_rcpf(1.f + __expf(-x)); }
; DEVI float softplusf(float x) { return x > 20.f ? x : __logf(1.f + __expf(x)); }
; DEVI float tanhfast(float x) { return 1.f - 2.f / (__expf(2.f * x) + 1.f); }
; DEVI int accrow(int r, int lane) { return (r & 3) + 8 * (r >> 2) + 4 * (lane >> 5); }
; template <int EPI>
; DEVI void gemm_epi(const Params& p, const GJob& jb, f32x16 (&acc)[2][2], int rbase, int cbase, int lane) {
;     ...
;       const int row = rbase + i * 32 + accrow(r, lane);
;       if (row < M) {
; #pragma unroll
;         for (int j = 0; j < 2; ++j) {
;           const int col = cbase + j * 32 + (lane & 31);
;           const float v = acc[i][j][r];
;           if (EPI == EPI_SSD_IN) {
;             if (col < 2048) ((bf16*)(ar + S_ZB))[(size_t)row * 2048 + col] = f2bf(v);
;             else if (col < 6144) ((bf16*)(ar + S_XBC))[(size_t)row * 4096 + col - 2048] = f2bf(v);
;             else if (col < 6176) ((float*)(ar + S_DTRAW))[(size_t)row * 32 + col - 6144] = v;
;           } else if (EPI == EPI_RESID) {
;             PW(bf16, W_Z)[(size_t)row * 1024 + col] = f2bf(ALPHA * bf2f(PW(bf16, W_Xb)[(size_t)row * 1024 + col]) + v);
;           } else if (EPI == EPI_GU) {
;             ((bf16*)(ar + F_GU))[(size_t)row * 5632 + col] = f2bf(v);
;           } else if (EPI == EPI_BF16) {
;             ((bf16*)jb.of)[(size_t)row * 1024 + col] = f2bf(v);
;           } else if (EPI == EPI_F32) {
;             jb.of[(size_t)row * 1024 + col] = v;
;           } else if (EPI == EPI_RK_W1) {
;             if (col < 64) ((bf16*)(ar + R_HW))[(size_t)row * 64 + col] = f2bf(tanhfast(v));
;           } else if (EPI == EPI_RK_A1) {
;             if (col < 64) ((bf16*)(ar + R_HA))[(size_t)row * 64 + col] = f2bf(v);
;           } else if (EPI == EPI_RK_G1) {
;             if (col < 192) ((bf16*)(ar + R_HG))[(size_t)row * 192 + col] = f2bf(col < 160 ? sigmf(v) : 0.f);
;           } else if (EPI == EPI_RK_W2) {
;             const float z = i_rk_w0[col] + v;
;             const float wl = -softplusf(-z) - 0.5f;
;             ((float*)(ar + R_W))[(size_t)row * 1024 + col] = __expf(-__expf(wl));
.LBB0_530:
	s_or_b64 exec, exec, s[2:3]
	v_or_b32_e32 v79, 17, v69
	v_or_b32_e32 v66, v79, v68
	v_cmp_gt_i32_e32 vcc, s90, v66
	s_and_saveexec_b64 s[2:3], vcc
	s_cbranch_execz .LBB0_532
	v_lshlrev_b64 v[80:81], 2, v[64:65]
	v_lshl_add_u64 v[82:83], s[8:9], 0, v[80:81]
	v_mov_b32_e32 v67, v170
	s_mov_b32 s5, 0x3f317217
	s_mov_b32 s18, 0x7f800000
	s_mov_b32 s4, 0xc1a00000
	v_add_f32_e32 v67, v41, v67
	v_mul_f32_e32 v84, 0xbfb8aa3b, v67
	v_exp_f32_e32 v84, v84
	s_nop 0
	v_add_f32_e32 v84, 1.0, v84
	v_cmp_gt_f32_e32 vcc, s69, v84
	s_nop 1
	v_cndmask_b32_e64 v85, 0, 32, vcc
	v_ldexp_f32 v84, v84, v85
	v_log_f32_e32 v84, v84
	v_cndmask_b32_e32 v85, 0, v216, vcc
	v_mul_f32_e32 v86, 0x3f317217, v84
	v_fma_f32 v86, v84, s5, -v86
	v_fmac_f32_e32 v86, 0x3377d1cf, v84
	v_fmac_f32_e32 v86, 0x3f317217, v84
	v_cmp_lt_f32_e64 vcc, |v84|, s18
	s_nop 1
	v_cndmask_b32_e32 v84, v84, v86, vcc
	v_sub_f32_e32 v84, v84, v85
	v_cmp_gt_f32_e32 vcc, s4, v67
	s_nop 1
	v_cndmask_b32_e64 v67, v84, -v67, vcc
	v_sub_f32_e32 v67, -0.5, v67
	v_mul_f32_e32 v67, 0x3fb8aa3b, v67
	v_exp_f32_e32 v84, v67
	v_ashrrev_i32_e32 v67, 31, v66
	v_lshlrev_b64 v[66:67], 12, v[66:67]
	v_lshl_add_u64 v[66:67], s[6:7], 0, v[66:67]
	v_mul_f32_e32 v84, 0xbfb8aa3b, v84
	v_exp_f32_e32 v84, v84
	v_lshl_add_u64 v[66:67], v[66:67], 0, v[80:81]
	global_store_dword v[66:67], v84, off
	v_mov_b32_e32 v80, v171
	v_add_f32_e32 v80, v57, v80
	v_mul_f32_e32 v81, 0xbfb8aa3b, v80
	v_exp_f32_e32 v81, v81
	s_nop 0
	v_add_f32_e32 v81, 1.0, v81
	v_cmp_gt_f32_e32 vcc, s69, v81
	s_nop 1
	v_cndmask_b32_e64 v82, 0, 32, vcc
	v_ldexp_f32 v81, v81, v82
	v_log_f32_e32 v81, v81
	v_cndmask_b32_e32 v82, 0, v216, vcc
	v_mul_f32_e32 v83, 0x3f317217, v81
	v_fma_f32 v83, v81, s5, -v83
	v_fmac_f32_e32 v83, 0x3377d1cf, v81
	v_fmac_f32_e32 v83, 0x3f317217, v81
	v_cmp_lt_f32_e64 vcc, |v81|, s18
	s_nop 1
	v_cndmask_b32_e32 v81, v81, v83, vcc
	v_sub_f32_e32 v81, v81, v82
	v_cmp_gt_f32_e32 vcc, s4, v80
	s_nop 1
	v_cndmask_b32_e64 v80, v81, -v80, vcc
	v_sub_f32_e32 v80, -0.5, v80
	v_mul_f32_e32 v80, 0x3fb8aa3b, v80
	v_exp_f32_e32 v80, v80
	s_nop 0
	v_mul_f32_e32 v80, 0xbfb8aa3b, v80
	v_exp_f32_e32 v80, v80
	global_store_dword v[66:67], v80, off offset:128
.LBB0_532:
	s_or_b64 exec, exec, s[2:3]
	s_waitcnt vmcnt(3)
	v_or_b32_e32 v80, 18, v69
	v_or_b32_e32 v66, v80, v68
	v_cmp_gt_i32_e32 vcc, s90, v66
	s_and_saveexec_b64 s[2:3], vcc
	s_cbranch_execz .LBB0_534
	v_lshlrev_b64 v[82:83], 2, v[64:65]
	v_lshl_add_u64 v[84:85], s[8:9], 0, v[82:83]
	v_mov_b32_e32 v67, v170
	s_mov_b32 s5, 0x3f317217
	s_mov_b32 s18, 0x7f800000
	s_mov_b32 s4, 0xc1a00000
	v_add_f32_e32 v67, v42, v67
	v_mul_f32_e32 v81, 0xbfb8aa3b, v67
	v_exp_f32_e32 v81, v81
	s_nop 0
	v_add_f32_e32 v81, 1.0, v81
	v_cmp_gt_f32_e32 vcc, s69, v81
	s_nop 1
	v_cndmask_b32_e64 v86, 0, 32, vcc
	v_ldexp_f32 v81, v81, v86
	v_log_f32_e32 v81, v81
	v_cndmask_b32_e32 v86, 0, v216, vcc
	v_mul_f32_e32 v87, 0x3f317217, v81
	v_fma_f32 v87, v81, s5, -v87
	v_fmac_f32_e32 v87, 0x3377d1cf, v81
	v_fmac_f32_e32 v87, 0x3f317217, v81
	v_cmp_lt_f32_e64 vcc, |v81|, s18
	s_nop 1
	v_cndmask_b32_e32 v81, v81, v87, vcc
	v_sub_f32_e32 v81, v81, v86
	v_cmp_gt_f32_e32 vcc, s4, v67
	s_nop 1
	v_cndmask_b32_e64 v67, v81, -v67, vcc
	v_sub_f32_e32 v67, -0.5, v67
	v_mul_f32_e32 v67, 0x3fb8aa3b, v67
	v_exp_f32_e32 v81, v67
	v_ashrrev_i32_e32 v67, 31, v66
	v_lshlrev_b64 v[66:67], 12, v[66:67]
	v_lshl_add_u64 v[66:67], s[6:7], 0, v[66:67]
	v_mul_f32_e32 v81, 0xbfb8aa3b, v81
	v_exp_f32_e32 v81, v81
	v_lshl_add_u64 v[66:67], v[66:67], 0, v[82:83]
	global_store_dword v[66:67], v81, off
	v_mov_b32_e32 v81, v171
	v_add_f32_e32 v81, v58, v81
	v_mul_f32_e32 v82, 0xbfb8aa3b, v81
	v_exp_f32_e32 v82, v82
	s_nop 0
	v_add_f32_e32 v82, 1.0, v82
	v_cmp_gt_f32_e32 vcc, s69, v82
	s_nop 1
	v_cndmask_b32_e64 v83, 0, 32, vcc
	v_ldexp_f32 v82, v82, v83
	v_log_f32_e32 v82, v82
	v_cndmask_b32_e32 v83, 0, v216, vcc
	v_mul_f32_e32 v84, 0x3f317217, v82
	v_fma_f32 v84, v82, s5, -v84
	v_fmac_f32_e32 v84, 0x3377d1cf, v82
	v_fmac_f32_e32 v84, 0x3f317217, v82
	v_cmp_lt_f32_e64 vcc, |v82|, s18
	s_nop 1
	v_cndmask_b32_e32 v82, v82, v84, vcc
	v_sub_f32_e32 v82, v82, v83
	v_cmp_gt_f32_e32 vcc, s4, v81
	s_nop 1
	v_cndmask_b32_e64 v81, v82, -v81, vcc
	v_sub_f32_e32 v81, -0.5, v81
	v_mul_f32_e32 v81, 0x3fb8aa3b, v81
	v_exp_f32_e32 v81, v81
	s_nop 0
	v_mul_f32_e32 v81, 0xbfb8aa3b, v81
	v_exp_f32_e32 v81, v81
	global_store_dword v[66:67], v81, off offset:128
.LBB0_534:
	s_or_b64 exec, exec, s[2:3]
	v_or_b32_e32 v81, 19, v70
	v_or_b32_e32 v66, v68, v81
	v_cmp_gt_i32_e32 vcc, s90, v66
	s_and_saveexec_b64 s[2:3], vcc
	s_cbranch_execz .LBB0_536
	v_lshlrev_b64 v[82:83], 2, v[64:65]
	v_lshl_add_u64 v[84:85], s[8:9], 0, v[82:83]
	v_mov_b32_e32 v67, v170
	s_mov_b32 s5, 0x3f317217
	s_mov_b32 s18, 0x7f800000
	s_mov_b32 s4, 0xc1a00000
	v_add_f32_e32 v67, v43, v67
	v_mul_f32_e32 v86, 0xbfb8aa3b, v67
	v_exp_f32_e32 v86, v86
	s_nop 0
	v_add_f32_e32 v86, 1.0, v86
	v_cmp_gt_f32_e32 vcc, s69, v86
	s_nop 1
	v_cndmask_b32_e64 v87, 0, 32, vcc
	v_ldexp_f32 v86, v86, v87
	v_log_f32_e32 v86, v86
	v_cndmask_b32_e32 v87, 0, v216, vcc
	v_mul_f32_e32 v88, 0x3f317217, v86
	v_fma_f32 v88, v86, s5, -v88
	v_fmac_f32_e32 v88, 0x3377d1cf, v86
	v_fmac_f32_e32 v88, 0x3f317217, v86
	v_cmp_lt_f32_e64 vcc, |v86|, s18
	s_nop 1
	v_cndmask_b32_e32 v86, v86, v88, vcc
	v_sub_f32_e32 v86, v86, v87
	v_cmp_gt_f32_e32 vcc, s4, v67
	s_nop 1
	v_cndmask_b32_e64 v67, v86, -v67, vcc
	v_sub_f32_e32 v67, -0.5, v67
	v_mul_f32_e32 v67, 0x3fb8aa3b, v67
	v_exp_f32_e32 v86, v67
	v_ashrrev_i32_e32 v67, 31, v66
	v_lshlrev_b64 v[66:67], 12, v[66:67]
	v_lshl_add_u64 v[66:67], s[6:7], 0, v[66:67]
	v_mul_f32_e32 v86, 0xbfb8aa3b, v86
	v_exp_f32_e32 v86, v86
	v_lshl_add_u64 v[66:67], v[66:67], 0, v[82:83]
	global_store_dword v[66:67], v86, off
	v_mov_b32_e32 v82, v171
	v_add_f32_e32 v82, v59, v82
	v_mul_f32_e32 v83, 0xbfb8aa3b, v82
	v_exp_f32_e32 v83, v83
	s_nop 0
	v_add_f32_e32 v83, 1.0, v83
	v_cmp_gt_f32_e32 vcc, s69, v83
	s_nop 1
	v_cndmask_b32_e64 v84, 0, 32, vcc
	v_ldexp_f32 v83, v83, v84
	v_log_f32_e32 v83, v83
	v_cndmask_b32_e32 v84, 0, v216, vcc
	v_mul_f32_e32 v85, 0x3f317217, v83
	v_fma_f32 v85, v83, s5, -v85
	v_fmac_f32_e32 v85, 0x3377d1cf, v83
	v_fmac_f32_e32 v85, 0x3f317217, v83
	v_cmp_lt_f32_e64 vcc, |v83|, s18
	s_nop 1
	v_cndmask_b32_e32 v83, v83, v85, vcc
	v_sub_f32_e32 v83, v83, v84
	v_cmp_gt_f32_e32 vcc, s4, v82
	s_nop 1
	v_cndmask_b32_e64 v82, v83, -v82, vcc
	v_sub_f32_e32 v82, -0.5, v82
	v_mul_f32_e32 v82, 0x3fb8aa3b, v82
	v_exp_f32_e32 v82, v82
	s_nop 0
	v_mul_f32_e32 v82, 0xbfb8aa3b, v82
	v_exp_f32_e32 v82, v82
	global_store_dword v[66:67], v82, off offset:128
; #define PW(T, off) ((T*)(lndp(p.ws) + (off)))
; DEVI float bf2f(bf16 h) { return __uint_as_float(((unsigned)h) << 16); }
; DEVI float sigmf(float x) { return __builtin_amdgcn_rcpf(1.f + __expf(-x)); }
; DEVI float softplusf(float x) { return x > 20.f ? x : __logf(1.f + __expf(x)); }
; DEVI float tanhfast(float x) { return 1.f - 2.f / (__expf(2.f * x) + 1.f); }
; DEVI int accrow(int r, int lane) { return (r & 3) + 8 * (r >> 2) + 4 * (lane >> 5); }
; template <int EPI>
; DEVI void gemm_epi(const Params& p, const GJob& jb, f32x16 (&acc)[2][2], int rbase, int cbase, int lane) {
;     ...
;       const int row = rbase + i * 32 + accrow(r, lane);
;       if (row < M) {
; #pragma unroll
;         for (int j = 0; j < 2; ++j) {
;           const int col = cbase + j * 32 + (lane & 31);
;           const float v = acc[i][j][r];
;           if (EPI == EPI_SSD_IN) {
;             if (col < 2048) ((bf16*)(ar + S_ZB))[(size_t)row * 2048 + col] = f2bf(v);
;             else if (col < 6144) ((bf16*)(ar + S_XBC))[(size_t)row * 4096 + col - 2048] = f2bf(v);
;             else if (col < 6176) ((float*)(ar + S_DTRAW))[(size_t)row * 32 + col - 6144] = v;
;           } else if (EPI == EPI_RESID) {
;             PW(bf16, W_Z)[(size_t)row * 1024 + col] = f2bf(ALPHA * bf2f(PW(bf16, W_Xb)[(size_t)row * 1024 + col]) + v);
;           } else if (EPI == EPI_GU) {
;             ((bf16*)(ar + F_GU))[(size_t)row * 5632 + col] = f2bf(v);
;           } else if (EPI == EPI_BF16) {
;             ((bf16*)jb.of)[(size_t)row * 1024 + col] = f2bf(v);
;           } else if (EPI == EPI_F32) {
;             jb.of[(size_t)row * 1024 + col] = v;
;           } else if (EPI == EPI_RK_W1) {
;             if (col < 64) ((bf16*)(ar + R_HW))[(size_t)row * 64 + col] = f2bf(tanhfast(v));
;           } else if (EPI == EPI_RK_A1) {
;             if (col < 64) ((bf16*)(ar + R_HA))[(size_t)row * 64 + col] = f2bf(v);
;           } else if (EPI == EPI_RK_G1) {
;             if (col < 192) ((bf16*)(ar + R_HG))[(size_t)row * 192 + col] = f2bf(col < 160 ? sigmf(v) : 0.f);
;           } else if (EPI == EPI_RK_W2) {
;             const float z = i_rk_w0[col] + v;
;             const float wl = -softplusf(-z) - 0.5f;
;             ((float*)(ar + R_W))[(size_t)row * 1024 + col] = __expf(-__expf(wl));
.LBB0_536:
	s_or_b64 exec, exec, s[2:3]
	v_or_b32_e32 v82, 24, v69
	v_or_b32_e32 v66, v82, v68
	v_cmp_gt_i32_e32 vcc, s90, v66
	s_and_saveexec_b64 s[2:3], vcc
	s_cbranch_execz .LBB0_538
	v_lshlrev_b64 v[84:85], 2, v[64:65]
	v_lshl_add_u64 v[86:87], s[8:9], 0, v[84:85]
	v_mov_b32_e32 v67, v170
	s_mov_b32 s5, 0x3f317217
	s_mov_b32 s18, 0x7f800000
	s_mov_b32 s4, 0xc1a00000
	v_add_f32_e32 v67, v44, v67
	v_mul_f32_e32 v83, 0xbfb8aa3b, v67
	v_exp_f32_e32 v83, v83
	s_nop 0
	v_add_f32_e32 v83, 1.0, v83
	v_cmp_gt_f32_e32 vcc, s69, v83
	s_nop 1
	v_cndmask_b32_e64 v88, 0, 32, vcc
	v_ldexp_f32 v83, v83, v88
	v_log_f32_e32 v83, v83
	v_cndmask_b32_e32 v88, 0, v216, vcc
	v_mul_f32_e32 v89, 0x3f317217, v83
	v_fma_f32 v89, v83, s5, -v89
	v_fmac_f32_e32 v89, 0x3377d1cf, v83
	v_fmac_f32_e32 v89, 0x3f317217, v83
	v_cmp_lt_f32_e64 vcc, |v83|, s18
	s_nop 1
	v_cndmask_b32_e32 v83, v83, v89, vcc
	v_sub_f32_e32 v83, v83, v88
	v_cmp_gt_f32_e32 vcc, s4, v67
	s_nop 1
	v_cndmask_b32_e64 v67, v83, -v67, vcc
	v_sub_f32_e32 v67, -0.5, v67
	v_mul_f32_e32 v67, 0x3fb8aa3b, v67
	v_exp_f32_e32 v83, v67
	v_ashrrev_i32_e32 v67, 31, v66
	v_lshlrev_b64 v[66:67], 12, v[66:67]
	v_lshl_add_u64 v[66:67], s[6:7], 0, v[66:67]
	v_mul_f32_e32 v83, 0xbfb8aa3b, v83
	v_exp_f32_e32 v83, v83
	v_lshl_add_u64 v[66:67], v[66:67], 0, v[84:85]
	global_store_dword v[66:67], v83, off
	v_mov_b32_e32 v83, v171
	v_add_f32_e32 v83, v60, v83
	v_mul_f32_e32 v84, 0xbfb8aa3b, v83
	v_exp_f32_e32 v84, v84
	s_nop 0
	v_add_f32_e32 v84, 1.0, v84
	v_cmp_gt_f32_e32 vcc, s69, v84
	s_nop 1
	v_cndmask_b32_e64 v85, 0, 32, vcc
	v_ldexp_f32 v84, v84, v85
	v_log_f32_e32 v84, v84
	v_cndmask_b32_e32 v85, 0, v216, vcc
	v_mul_f32_e32 v86, 0x3f317217, v84
	v_fma_f32 v86, v84, s5, -v86
	v_fmac_f32_e32 v86, 0x3377d1cf, v84
	v_fmac_f32_e32 v86, 0x3f317217, v84
	v_cmp_lt_f32_e64 vcc, |v84|, s18
	s_nop 1
	v_cndmask_b32_e32 v84, v84, v86, vcc
	v_sub_f32_e32 v84, v84, v85
	v_cmp_gt_f32_e32 vcc, s4, v83
	s_nop 1
	v_cndmask_b32_e64 v83, v84, -v83, vcc
	v_sub_f32_e32 v83, -0.5, v83
	v_mul_f32_e32 v83, 0x3fb8aa3b, v83
	v_exp_f32_e32 v83, v83
	s_nop 0
	v_mul_f32_e32 v83, 0xbfb8aa3b, v83
	v_exp_f32_e32 v83, v83
	global_store_dword v[66:67], v83, off offset:128
.LBB0_538:
	s_or_b64 exec, exec, s[2:3]
	v_or_b32_e32 v83, 25, v69
	v_or_b32_e32 v66, v83, v68
	v_cmp_gt_i32_e32 vcc, s90, v66
	s_and_saveexec_b64 s[2:3], vcc
	s_cbranch_execz .LBB0_540
	v_lshlrev_b64 v[84:85], 2, v[64:65]
	v_lshl_add_u64 v[86:87], s[8:9], 0, v[84:85]
	v_mov_b32_e32 v67, v170
	s_mov_b32 s5, 0x3f317217
	s_mov_b32 s18, 0x7f800000
	s_mov_b32 s4, 0xc1a00000
	v_add_f32_e32 v67, v45, v67
	v_mul_f32_e32 v88, 0xbfb8aa3b, v67
	v_exp_f32_e32 v88, v88
	s_nop 0
	v_add_f32_e32 v88, 1.0, v88
	v_cmp_gt_f32_e32 vcc, s69, v88
	s_nop 1
	v_cndmask_b32_e64 v89, 0, 32, vcc
	v_ldexp_f32 v88, v88, v89
	v_log_f32_e32 v88, v88
	v_cndmask_b32_e32 v89, 0, v216, vcc
	v_mul_f32_e32 v90, 0x3f317217, v88
	v_fma_f32 v90, v88, s5, -v90
	v_fmac_f32_e32 v90, 0x3377d1cf, v88
	v_fmac_f32_e32 v90, 0x3f317217, v88
	v_cmp_lt_f32_e64 vcc, |v88|, s18
	s_nop 1
	v_cndmask_b32_e32 v88, v88, v90, vcc
	v_sub_f32_e32 v88, v88, v89
	v_cmp_gt_f32_e32 vcc, s4, v67
	s_nop 1
	v_cndmask_b32_e64 v67, v88, -v67, vcc
	v_sub_f32_e32 v67, -0.5, v67
	v_mul_f32_e32 v67, 0x3fb8aa3b, v67
	v_exp_f32_e32 v88, v67
	v_ashrrev_i32_e32 v67, 31, v66
	v_lshlrev_b64 v[66:67], 12, v[66:67]
	v_lshl_add_u64 v[66:67], s[6:7], 0, v[66:67]
	v_mul_f32_e32 v88, 0xbfb8aa3b, v88
	v_exp_f32_e32 v88, v88
	v_lshl_add_u64 v[66:67], v[66:67], 0, v[84:85]
	global_store_dword v[66:67], v88, off
	v_mov_b32_e32 v84, v171
	v_add_f32_e32 v84, v61, v84
	v_mul_f32_e32 v85, 0xbfb8aa3b, v84
	v_exp_f32_e32 v85, v85
	s_nop 0
	v_add_f32_e32 v85, 1.0, v85
	v_cmp_gt_f32_e32 vcc, s69, v85
	s_nop 1
	v_cndmask_b32_e64 v86, 0, 32, vcc
	v_ldexp_f32 v85, v85, v86
	v_log_f32_e32 v85, v85
	v_cndmask_b32_e32 v86, 0, v216, vcc
	v_mul_f32_e32 v87, 0x3f317217, v85
	v_fma_f32 v87, v85, s5, -v87
	v_fmac_f32_e32 v87, 0x3377d1cf, v85
	v_fmac_f32_e32 v87, 0x3f317217, v85
	v_cmp_lt_f32_e64 vcc, |v85|, s18
	s_nop 1
	v_cndmask_b32_e32 v85, v85, v87, vcc
	v_sub_f32_e32 v85, v85, v86
	v_cmp_gt_f32_e32 vcc, s4, v84
	s_nop 1
	v_cndmask_b32_e64 v84, v85, -v84, vcc
	v_sub_f32_e32 v84, -0.5, v84
	v_mul_f32_e32 v84, 0x3fb8aa3b, v84
	v_exp_f32_e32 v84, v84
	s_nop 0
	v_mul_f32_e32 v84, 0xbfb8aa3b, v84
	v_exp_f32_e32 v84, v84
	global_store_dword v[66:67], v84, off offset:128
.LBB0_540:
	s_or_b64 exec, exec, s[2:3]
	s_waitcnt vmcnt(2)
	v_or_b32_e32 v84, 26, v69
	v_or_b32_e32 v66, v84, v68
	v_cmp_gt_i32_e32 vcc, s90, v66
	s_and_saveexec_b64 s[2:3], vcc
	s_cbranch_execz .LBB0_542
	v_lshlrev_b64 v[86:87], 2, v[64:65]
	v_lshl_add_u64 v[88:89], s[8:9], 0, v[86:87]
	v_mov_b32_e32 v67, v170
	s_mov_b32 s5, 0x3f317217
	s_mov_b32 s18, 0x7f800000
	s_mov_b32 s4, 0xc1a00000
	v_add_f32_e32 v67, v46, v67
	v_mul_f32_e32 v85, 0xbfb8aa3b, v67
	v_exp_f32_e32 v85, v85
	s_nop 0
	v_add_f32_e32 v85, 1.0, v85
	v_cmp_gt_f32_e32 vcc, s69, v85
	s_nop 1
	v_cndmask_b32_e64 v90, 0, 32, vcc
	v_ldexp_f32 v85, v85, v90
	v_log_f32_e32 v85, v85
	v_cndmask_b32_e32 v90, 0, v216, vcc
	v_mul_f32_e32 v91, 0x3f317217, v85
	v_fma_f32 v91, v85, s5, -v91
	v_fmac_f32_e32 v91, 0x3377d1cf, v85
	v_fmac_f32_e32 v91, 0x3f317217, v85
	v_cmp_lt_f32_e64 vcc, |v85|, s18
	s_nop 1
	v_cndmask_b32_e32 v85, v85, v91, vcc
	v_sub_f32_e32 v85, v85, v90
	v_cmp_gt_f32_e32 vcc, s4, v67
	s_nop 1
	v_cndmask_b32_e64 v67, v85, -v67, vcc
	v_sub_f32_e32 v67, -0.5, v67
	v_mul_f32_e32 v67, 0x3fb8aa3b, v67
	v_exp_f32_e32 v85, v67
	v_ashrrev_i32_e32 v67, 31, v66
	v_lshlrev_b64 v[66:67], 12, v[66:67]
	v_lshl_add_u64 v[66:67], s[6:7], 0, v[66:67]
	v_mul_f32_e32 v85, 0xbfb8aa3b, v85
	v_exp_f32_e32 v85, v85
	v_lshl_add_u64 v[66:67], v[66:67], 0, v[86:87]
	global_store_dword v[66:67], v85, off
	v_mov_b32_e32 v85, v171
	v_add_f32_e32 v85, v62, v85
	v_mul_f32_e32 v86, 0xbfb8aa3b, v85
	v_exp_f32_e32 v86, v86
	s_nop 0
	v_add_f32_e32 v86, 1.0, v86
	v_cmp_gt_f32_e32 vcc, s69, v86
	s_nop 1
	v_cndmask_b32_e64 v87, 0, 32, vcc
	v_ldexp_f32 v86, v86, v87
	v_log_f32_e32 v86, v86
	v_cndmask_b32_e32 v87, 0, v216, vcc
	v_mul_f32_e32 v88, 0x3f317217, v86
	v_fma_f32 v88, v86, s5, -v88
	v_fmac_f32_e32 v88, 0x3377d1cf, v86
	v_fmac_f32_e32 v88, 0x3f317217, v86
	v_cmp_lt_f32_e64 vcc, |v86|, s18
	s_nop 1
	v_cndmask_b32_e32 v86, v86, v88, vcc
	v_sub_f32_e32 v86, v86, v87
	v_cmp_gt_f32_e32 vcc, s4, v85
	s_nop 1
	v_cndmask_b32_e64 v85, v86, -v85, vcc
	v_sub_f32_e32 v85, -0.5, v85
	v_mul_f32_e32 v85, 0x3fb8aa3b, v85
	v_exp_f32_e32 v85, v85
	s_nop 0
	v_mul_f32_e32 v85, 0xbfb8aa3b, v85
	v_exp_f32_e32 v85, v85
	global_store_dword v[66:67], v85, off offset:128
; #define PW(T, off) ((T*)(lndp(p.ws) + (off)))
; DEVI float bf2f(bf16 h) { return __uint_as_float(((unsigned)h) << 16); }
; DEVI float sigmf(float x) { return __builtin_amdgcn_rcpf(1.f + __expf(-x)); }
; DEVI float softplusf(float x) { return x > 20.f ? x : __logf(1.f + __expf(x)); }
; DEVI float tanhfast(float x) { return 1.f - 2.f / (__expf(2.f * x) + 1.f); }
; DEVI int accrow(int r, int lane) { return (r & 3) + 8 * (r >> 2) + 4 * (lane >> 5); }
; template <int EPI>
; DEVI void gemm_epi(const Params& p, const GJob& jb, f32x16 (&acc)[2][2], int rbase, int cbase, int lane) {
;     ...
;       const int row = rbase + i * 32 + accrow(r, lane);
;       if (row < M) {
; #pragma unroll
;         for (int j = 0; j < 2; ++j) {
;           const int col = cbase + j * 32 + (lane & 31);
;           const float v = acc[i][j][r];
;           if (EPI == EPI_SSD_IN) {
;             if (col < 2048) ((bf16*)(ar + S_ZB))[(size_t)row * 2048 + col] = f2bf(v);
;             else if (col < 6144) ((bf16*)(ar + S_XBC))[(size_t)row * 4096 + col - 2048] = f2bf(v);
;             else if (col < 6176) ((float*)(ar + S_DTRAW))[(size_t)row * 32 + col - 6144] = v;
;           } else if (EPI == EPI_RESID) {
;             PW(bf16, W_Z)[(size_t)row * 1024 + col] = f2bf(ALPHA * bf2f(PW(bf16, W_Xb)[(size_t)row * 1024 + col]) + v);
;           } else if (EPI == EPI_GU) {
;             ((bf16*)(ar + F_GU))[(size_t)row * 5632 + col] = f2bf(v);
;           } else if (EPI == EPI_BF16) {
;             ((bf16*)jb.of)[(size_t)row * 1024 + col] = f2bf(v);
;           } else if (EPI == EPI_F32) {
;             jb.of[(size_t)row * 1024 + col] = v;
;           } else if (EPI == EPI_RK_W1) {
;             if (col < 64) ((bf16*)(ar + R_HW))[(size_t)row * 64 + col] = f2bf(tanhfast(v));
;           } else if (EPI == EPI_RK_A1) {
;             if (col < 64) ((bf16*)(ar + R_HA))[(size_t)row * 64 + col] = f2bf(v);
;           } else if (EPI == EPI_RK_G1) {
;             if (col < 192) ((bf16*)(ar + R_HG))[(size_t)row * 192 + col] = f2bf(col < 160 ? sigmf(v) : 0.f);
;           } else if (EPI == EPI_RK_W2) {
;             const float z = i_rk_w0[col] + v;
;             const float wl = -softplusf(-z) - 0.5f;
;             ((float*)(ar + R_W))[(size_t)row * 1024 + col] = __expf(-__expf(wl));
.LBB0_542:
	s_or_b64 exec, exec, s[2:3]
	v_or_b32_e32 v85, 27, v70
	v_or_b32_e32 v66, v68, v85
	v_cmp_gt_i32_e32 vcc, s90, v66
	s_and_saveexec_b64 s[2:3], vcc
	s_cbranch_execz .LBB0_544
	v_lshlrev_b64 v[86:87], 2, v[64:65]
	v_lshl_add_u64 v[88:89], s[8:9], 0, v[86:87]
	v_mov_b32_e32 v67, v170
	s_mov_b32 s5, 0x3f317217
	s_mov_b32 s18, 0x7f800000
	s_mov_b32 s4, 0xc1a00000
	v_add_f32_e32 v67, v47, v67
	v_mul_f32_e32 v90, 0xbfb8aa3b, v67
	v_exp_f32_e32 v90, v90
	s_nop 0
	v_add_f32_e32 v90, 1.0, v90
	v_cmp_gt_f32_e32 vcc, s69, v90
	s_nop 1
	v_cndmask_b32_e64 v91, 0, 32, vcc
	v_ldexp_f32 v90, v90, v91
	v_log_f32_e32 v90, v90
	v_cndmask_b32_e32 v91, 0, v216, vcc
	v_mul_f32_e32 v92, 0x3f317217, v90
	v_fma_f32 v92, v90, s5, -v92
	v_fmac_f32_e32 v92, 0x3377d1cf, v90
	v_fmac_f32_e32 v92, 0x3f317217, v90
	v_cmp_lt_f32_e64 vcc, |v90|, s18
	s_nop 1
	v_cndmask_b32_e32 v90, v90, v92, vcc
	v_sub_f32_e32 v90, v90, v91
	v_cmp_gt_f32_e32 vcc, s4, v67
	s_nop 1
	v_cndmask_b32_e64 v67, v90, -v67, vcc
	v_sub_f32_e32 v67, -0.5, v67
	v_mul_f32_e32 v67, 0x3fb8aa3b, v67
	v_exp_f32_e32 v90, v67
	v_ashrrev_i32_e32 v67, 31, v66
	v_lshlrev_b64 v[66:67], 12, v[66:67]
	v_lshl_add_u64 v[66:67], s[6:7], 0, v[66:67]
	v_mul_f32_e32 v90, 0xbfb8aa3b, v90
	v_exp_f32_e32 v90, v90
	v_lshl_add_u64 v[66:67], v[66:67], 0, v[86:87]
	global_store_dword v[66:67], v90, off
	v_mov_b32_e32 v86, v171
	v_add_f32_e32 v86, v63, v86
	v_mul_f32_e32 v87, 0xbfb8aa3b, v86
	v_exp_f32_e32 v87, v87
	s_nop 0
	v_add_f32_e32 v87, 1.0, v87
	v_cmp_gt_f32_e32 vcc, s69, v87
	s_nop 1
	v_cndmask_b32_e64 v88, 0, 32, vcc
	v_ldexp_f32 v87, v87, v88
	v_log_f32_e32 v87, v87
	v_cndmask_b32_e32 v88, 0, v216, vcc
	v_mul_f32_e32 v89, 0x3f317217, v87
	v_fma_f32 v89, v87, s5, -v89
	v_fmac_f32_e32 v89, 0x3377d1cf, v87
	v_fmac_f32_e32 v89, 0x3f317217, v87
	v_cmp_lt_f32_e64 vcc, |v87|, s18
	s_nop 1
	v_cndmask_b32_e32 v87, v87, v89, vcc
	v_sub_f32_e32 v87, v87, v88
	v_cmp_gt_f32_e32 vcc, s4, v86
	s_nop 1
	v_cndmask_b32_e64 v86, v87, -v86, vcc
	v_sub_f32_e32 v86, -0.5, v86
	v_mul_f32_e32 v86, 0x3fb8aa3b, v86
	v_exp_f32_e32 v86, v86
	s_nop 0
	v_mul_f32_e32 v86, 0xbfb8aa3b, v86
	v_exp_f32_e32 v86, v86
	global_store_dword v[66:67], v86, off offset:128
.LBB0_544:
	s_or_b64 exec, exec, s[2:3]
	v_or_b32_e32 v86, 32, v68
	v_or_b32_e32 v66, v86, v69
	v_cmp_gt_i32_e32 vcc, s90, v66
	s_and_saveexec_b64 s[2:3], vcc
	s_cbranch_execz .LBB0_546
	v_lshlrev_b64 v[88:89], 2, v[64:65]
	v_lshl_add_u64 v[90:91], s[8:9], 0, v[88:89]
	v_mov_b32_e32 v67, v170
	s_mov_b32 s5, 0x3f317217
	s_mov_b32 s18, 0x7f800000
	s_mov_b32 s4, 0xc1a00000
	v_add_f32_e32 v67, v16, v67
	v_mul_f32_e32 v87, 0xbfb8aa3b, v67
	v_exp_f32_e32 v87, v87
	s_nop 0
	v_add_f32_e32 v87, 1.0, v87
	v_cmp_gt_f32_e32 vcc, s69, v87
	s_nop 1
	v_cndmask_b32_e64 v92, 0, 32, vcc
	v_ldexp_f32 v87, v87, v92
	v_log_f32_e32 v87, v87
	v_cndmask_b32_e32 v92, 0, v216, vcc
	v_mul_f32_e32 v93, 0x3f317217, v87
	v_fma_f32 v93, v87, s5, -v93
	v_fmac_f32_e32 v93, 0x3377d1cf, v87
	v_fmac_f32_e32 v93, 0x3f317217, v87
	v_cmp_lt_f32_e64 vcc, |v87|, s18
	s_nop 1
	v_cndmask_b32_e32 v87, v87, v93, vcc
	v_sub_f32_e32 v87, v87, v92
	v_cmp_gt_f32_e32 vcc, s4, v67
	s_nop 1
	v_cndmask_b32_e64 v67, v87, -v67, vcc
	v_sub_f32_e32 v67, -0.5, v67
	v_mul_f32_e32 v67, 0x3fb8aa3b, v67
	v_exp_f32_e32 v87, v67
	v_ashrrev_i32_e32 v67, 31, v66
	v_lshlrev_b64 v[66:67], 12, v[66:67]
	v_lshl_add_u64 v[66:67], s[6:7], 0, v[66:67]
	v_mul_f32_e32 v87, 0xbfb8aa3b, v87
	v_exp_f32_e32 v87, v87
	v_lshl_add_u64 v[66:67], v[66:67], 0, v[88:89]
	global_store_dword v[66:67], v87, off
	v_mov_b32_e32 v87, v171
	v_add_f32_e32 v87, v0, v87
	v_mul_f32_e32 v88, 0xbfb8aa3b, v87
	v_exp_f32_e32 v88, v88
	s_nop 0
	v_add_f32_e32 v88, 1.0, v88
	v_cmp_gt_f32_e32 vcc, s69, v88
	s_nop 1
	v_cndmask_b32_e64 v89, 0, 32, vcc
	v_ldexp_f32 v88, v88, v89
	v_log_f32_e32 v88, v88
	v_cndmask_b32_e32 v89, 0, v216, vcc
	v_mul_f32_e32 v90, 0x3f317217, v88
	v_fma_f32 v90, v88, s5, -v90
	v_fmac_f32_e32 v90, 0x3377d1cf, v88
	v_fmac_f32_e32 v90, 0x3f317217, v88
	v_cmp_lt_f32_e64 vcc, |v88|, s18
	s_nop 1
	v_cndmask_b32_e32 v88, v88, v90, vcc
	v_sub_f32_e32 v88, v88, v89
	v_cmp_gt_f32_e32 vcc, s4, v87
	s_nop 1
	v_cndmask_b32_e64 v87, v88, -v87, vcc
	v_sub_f32_e32 v87, -0.5, v87
	v_mul_f32_e32 v87, 0x3fb8aa3b, v87
	v_exp_f32_e32 v87, v87
	s_nop 0
	v_mul_f32_e32 v87, 0xbfb8aa3b, v87
	v_exp_f32_e32 v87, v87
	global_store_dword v[66:67], v87, off offset:128
.LBB0_546:
	s_or_b64 exec, exec, s[2:3]
	v_or_b32_e32 v66, v86, v71
	v_cmp_gt_i32_e32 vcc, s90, v66
	s_and_saveexec_b64 s[2:3], vcc
	s_cbranch_execz .LBB0_548
	v_lshlrev_b64 v[88:89], 2, v[64:65]
	v_lshl_add_u64 v[90:91], s[8:9], 0, v[88:89]
	v_mov_b32_e32 v67, v170
	s_mov_b32 s5, 0x3f317217
	s_mov_b32 s18, 0x7f800000
	s_mov_b32 s4, 0xc1a00000
	v_add_f32_e32 v67, v17, v67
	v_mul_f32_e32 v71, 0xbfb8aa3b, v67
	v_exp_f32_e32 v71, v71
	s_nop 0
	v_add_f32_e32 v71, 1.0, v71
	v_cmp_gt_f32_e32 vcc, s69, v71
	s_nop 1
	v_cndmask_b32_e64 v87, 0, 32, vcc
	v_ldexp_f32 v71, v71, v87
	v_log_f32_e32 v71, v71
	v_cndmask_b32_e32 v87, 0, v216, vcc
	v_mul_f32_e32 v92, 0x3f317217, v71
	v_fma_f32 v92, v71, s5, -v92
	v_fmac_f32_e32 v92, 0x3377d1cf, v71
	v_fmac_f32_e32 v92, 0x3f317217, v71
	v_cmp_lt_f32_e64 vcc, |v71|, s18
	s_nop 1
	v_cndmask_b32_e32 v71, v71, v92, vcc
	v_sub_f32_e32 v71, v71, v87
	v_cmp_gt_f32_e32 vcc, s4, v67
	s_nop 1
	v_cndmask_b32_e64 v67, v71, -v67, vcc
	v_sub_f32_e32 v67, -0.5, v67
	v_mul_f32_e32 v67, 0x3fb8aa3b, v67
	v_exp_f32_e32 v71, v67
	v_ashrrev_i32_e32 v67, 31, v66
	v_lshlrev_b64 v[66:67], 12, v[66:67]
	v_lshl_add_u64 v[66:67], s[6:7], 0, v[66:67]
	v_mul_f32_e32 v71, 0xbfb8aa3b, v71
	v_exp_f32_e32 v71, v71
	v_lshl_add_u64 v[66:67], v[66:67], 0, v[88:89]
	global_store_dword v[66:67], v71, off
	v_mov_b32_e32 v71, v171
	v_add_f32_e32 v71, v1, v71
	v_mul_f32_e32 v87, 0xbfb8aa3b, v71
	v_exp_f32_e32 v87, v87
	s_nop 0
	v_add_f32_e32 v87, 1.0, v87
	v_cmp_gt_f32_e32 vcc, s69, v87
	s_nop 1
	v_cndmask_b32_e64 v88, 0, 32, vcc
	v_ldexp_f32 v87, v87, v88
	v_log_f32_e32 v87, v87
	v_cndmask_b32_e32 v88, 0, v216, vcc
	v_mul_f32_e32 v89, 0x3f317217, v87
	v_fma_f32 v89, v87, s5, -v89
	v_fmac_f32_e32 v89, 0x3377d1cf, v87
	v_fmac_f32_e32 v89, 0x3f317217, v87
	v_cmp_lt_f32_e64 vcc, |v87|, s18
	s_nop 1
	v_cndmask_b32_e32 v87, v87, v89, vcc
	v_sub_f32_e32 v87, v87, v88
	v_cmp_gt_f32_e32 vcc, s4, v71
	s_nop 1
	v_cndmask_b32_e64 v71, v87, -v71, vcc
	v_sub_f32_e32 v71, -0.5, v71
	v_mul_f32_e32 v71, 0x3fb8aa3b, v71
	v_exp_f32_e32 v71, v71
	s_nop 0
	v_mul_f32_e32 v71, 0xbfb8aa3b, v71
	v_exp_f32_e32 v71, v71
	global_store_dword v[66:67], v71, off offset:128
; #define PW(T, off) ((T*)(lndp(p.ws) + (off)))
; DEVI float bf2f(bf16 h) { return __uint_as_float(((unsigned)h) << 16); }
; DEVI float sigmf(float x) { return __builtin_amdgcn_rcpf(1.f + __expf(-x)); }
; DEVI float softplusf(float x) { return x > 20.f ? x : __logf(1.f + __expf(x)); }
; DEVI float tanhfast(float x) { return 1.f - 2.f / (__expf(2.f * x) + 1.f); }
; DEVI int accrow(int r, int lane) { return (r & 3) + 8 * (r >> 2) + 4 * (lane >> 5); }
; template <int EPI>
; DEVI void gemm_epi(const Params& p, const GJob& jb, f32x16 (&acc)[2][2], int rbase, int cbase, int lane) {
;     ...
;       const int row = rbase + i * 32 + accrow(r, lane);
;       if (row < M) {
; #pragma unroll
;         for (int j = 0; j < 2; ++j) {
;           const int col = cbase + j * 32 + (lane & 31);
;           const float v = acc[i][j][r];
;           if (EPI == EPI_SSD_IN) {
;             if (col < 2048) ((bf16*)(ar + S_ZB))[(size_t)row * 2048 + col] = f2bf(v);
;             else if (col < 6144) ((bf16*)(ar + S_XBC))[(size_t)row * 4096 + col - 2048] = f2bf(v);
;             else if (col < 6176) ((float*)(ar + S_DTRAW))[(size_t)row * 32 + col - 6144] = v;
;           } else if (EPI == EPI_RESID) {
;             PW(bf16, W_Z)[(size_t)row * 1024 + col] = f2bf(ALPHA * bf2f(PW(bf16, W_Xb)[(size_t)row * 1024 + col]) + v);
;           } else if (EPI == EPI_GU) {
;             ((bf16*)(ar + F_GU))[(size_t)row * 5632 + col] = f2bf(v);
;           } else if (EPI == EPI_BF16) {
;             ((bf16*)jb.of)[(size_t)row * 1024 + col] = f2bf(v);
;           } else if (EPI == EPI_F32) {
;             jb.of[(size_t)row * 1024 + col] = v;
;           } else if (EPI == EPI_RK_W1) {
;             if (col < 64) ((bf16*)(ar + R_HW))[(size_t)row * 64 + col] = f2bf(tanhfast(v));
;           } else if (EPI == EPI_RK_A1) {
;             if (col < 64) ((bf16*)(ar + R_HA))[(size_t)row * 64 + col] = f2bf(v);
;           } else if (EPI == EPI_RK_G1) {
;             if (col < 192) ((bf16*)(ar + R_HG))[(size_t)row * 192 + col] = f2bf(col < 160 ? sigmf(v) : 0.f);
;           } else if (EPI == EPI_RK_W2) {
;             const float z = i_rk_w0[col] + v;
;             const float wl = -softplusf(-z) - 0.5f;
;             ((float*)(ar + R_W))[(size_t)row * 1024 + col] = __expf(-__expf(wl));
.LBB0_548:
	s_or_b64 exec, exec, s[2:3]
	v_or_b32_e32 v66, v86, v72
	v_cmp_gt_i32_e32 vcc, s90, v66
	s_and_saveexec_b64 s[2:3], vcc
	s_cbranch_execz .LBB0_550
	v_lshlrev_b64 v[88:89], 2, v[64:65]
	v_lshl_add_u64 v[90:91], s[8:9], 0, v[88:89]
	v_mov_b32_e32 v67, v170
	s_mov_b32 s5, 0x3f317217
	s_mov_b32 s18, 0x7f800000
	s_mov_b32 s4, 0xc1a00000
	v_add_f32_e32 v67, v18, v67
	v_mul_f32_e32 v71, 0xbfb8aa3b, v67
	v_exp_f32_e32 v71, v71
	s_nop 0
	v_add_f32_e32 v71, 1.0, v71
	v_cmp_gt_f32_e32 vcc, s69, v71
	s_nop 1
	v_cndmask_b32_e64 v72, 0, 32, vcc
	v_ldexp_f32 v71, v71, v72
	v_log_f32_e32 v71, v71
	v_cndmask_b32_e32 v72, 0, v216, vcc
	v_mul_f32_e32 v87, 0x3f317217, v71
	v_fma_f32 v87, v71, s5, -v87
	v_fmac_f32_e32 v87, 0x3377d1cf, v71
	v_fmac_f32_e32 v87, 0x3f317217, v71
	v_cmp_lt_f32_e64 vcc, |v71|, s18
	s_nop 1
	v_cndmask_b32_e32 v71, v71, v87, vcc
	v_sub_f32_e32 v71, v71, v72
	v_cmp_gt_f32_e32 vcc, s4, v67
	s_nop 1
	v_cndmask_b32_e64 v67, v71, -v67, vcc
	v_sub_f32_e32 v67, -0.5, v67
	v_mul_f32_e32 v67, 0x3fb8aa3b, v67
	v_exp_f32_e32 v71, v67
	v_ashrrev_i32_e32 v67, 31, v66
	v_lshlrev_b64 v[66:67], 12, v[66:67]
	v_lshl_add_u64 v[66:67], s[6:7], 0, v[66:67]
	v_mul_f32_e32 v71, 0xbfb8aa3b, v71
	v_exp_f32_e32 v71, v71
	v_lshl_add_u64 v[66:67], v[66:67], 0, v[88:89]
	global_store_dword v[66:67], v71, off
	v_mov_b32_e32 v71, v171
	v_add_f32_e32 v71, v2, v71
	v_mul_f32_e32 v72, 0xbfb8aa3b, v71
	v_exp_f32_e32 v72, v72
	s_nop 0
	v_add_f32_e32 v72, 1.0, v72
	v_cmp_gt_f32_e32 vcc, s69, v72
	s_nop 1
	v_cndmask_b32_e64 v87, 0, 32, vcc
	v_ldexp_f32 v72, v72, v87
	v_log_f32_e32 v72, v72
	v_cndmask_b32_e32 v87, 0, v216, vcc
	v_mul_f32_e32 v88, 0x3f317217, v72
	v_fma_f32 v88, v72, s5, -v88
	v_fmac_f32_e32 v88, 0x3377d1cf, v72
	v_fmac_f32_e32 v88, 0x3f317217, v72
	v_cmp_lt_f32_e64 vcc, |v72|, s18
	s_nop 1
	v_cndmask_b32_e32 v72, v72, v88, vcc
	v_sub_f32_e32 v72, v72, v87
	v_cmp_gt_f32_e32 vcc, s4, v71
	s_nop 1
	v_cndmask_b32_e64 v71, v72, -v71, vcc
	v_sub_f32_e32 v71, -0.5, v71
	v_mul_f32_e32 v71, 0x3fb8aa3b, v71
	v_exp_f32_e32 v71, v71
	s_nop 0
	v_mul_f32_e32 v71, 0xbfb8aa3b, v71
	v_exp_f32_e32 v71, v71
	global_store_dword v[66:67], v71, off offset:128
.LBB0_550:
	s_or_b64 exec, exec, s[2:3]
	v_or_b32_e32 v66, v86, v73
	v_cmp_gt_i32_e32 vcc, s90, v66
	s_and_saveexec_b64 s[2:3], vcc
	s_cbranch_execz .LBB0_552
	v_lshlrev_b64 v[72:73], 2, v[64:65]
	v_lshl_add_u64 v[88:89], s[8:9], 0, v[72:73]
	v_mov_b32_e32 v67, v170
	s_mov_b32 s5, 0x3f317217
	s_mov_b32 s18, 0x7f800000
	s_mov_b32 s4, 0xc1a00000
	v_add_f32_e32 v67, v19, v67
	v_mul_f32_e32 v71, 0xbfb8aa3b, v67
	v_exp_f32_e32 v71, v71
	s_nop 0
	v_add_f32_e32 v71, 1.0, v71
	v_cmp_gt_f32_e32 vcc, s69, v71
	s_nop 1
	v_cndmask_b32_e64 v87, 0, 32, vcc
	v_ldexp_f32 v71, v71, v87
	v_log_f32_e32 v71, v71
	v_cndmask_b32_e32 v87, 0, v216, vcc
	v_mul_f32_e32 v90, 0x3f317217, v71
	v_fma_f32 v90, v71, s5, -v90
	v_fmac_f32_e32 v90, 0x3377d1cf, v71
	v_fmac_f32_e32 v90, 0x3f317217, v71
	v_cmp_lt_f32_e64 vcc, |v71|, s18
	s_nop 1
	v_cndmask_b32_e32 v71, v71, v90, vcc
	v_sub_f32_e32 v71, v71, v87
	v_cmp_gt_f32_e32 vcc, s4, v67
	s_nop 1
	v_cndmask_b32_e64 v67, v71, -v67, vcc
	v_sub_f32_e32 v67, -0.5, v67
	v_mul_f32_e32 v67, 0x3fb8aa3b, v67
	v_exp_f32_e32 v71, v67
	v_ashrrev_i32_e32 v67, 31, v66
	v_lshlrev_b64 v[66:67], 12, v[66:67]
	v_lshl_add_u64 v[66:67], s[6:7], 0, v[66:67]
	v_mul_f32_e32 v71, 0xbfb8aa3b, v71
	v_exp_f32_e32 v71, v71
	v_lshl_add_u64 v[66:67], v[66:67], 0, v[72:73]
	global_store_dword v[66:67], v71, off
	v_mov_b32_e32 v71, v171
	v_add_f32_e32 v71, v3, v71
	v_mul_f32_e32 v72, 0xbfb8aa3b, v71
	v_exp_f32_e32 v72, v72
	s_nop 0
	v_add_f32_e32 v72, 1.0, v72
	v_cmp_gt_f32_e32 vcc, s69, v72
	s_nop 1
	v_cndmask_b32_e64 v73, 0, 32, vcc
	v_ldexp_f32 v72, v72, v73
	v_log_f32_e32 v72, v72
	v_cndmask_b32_e32 v73, 0, v216, vcc
	v_mul_f32_e32 v87, 0x3f317217, v72
	v_fma_f32 v87, v72, s5, -v87
	v_fmac_f32_e32 v87, 0x3377d1cf, v72
	v_fmac_f32_e32 v87, 0x3f317217, v72
	v_cmp_lt_f32_e64 vcc, |v72|, s18
	s_nop 1
	v_cndmask_b32_e32 v72, v72, v87, vcc
	v_sub_f32_e32 v72, v72, v73
	v_cmp_gt_f32_e32 vcc, s4, v71
	s_nop 1
	v_cndmask_b32_e64 v71, v72, -v71, vcc
	v_sub_f32_e32 v71, -0.5, v71
	v_mul_f32_e32 v71, 0x3fb8aa3b, v71
	v_exp_f32_e32 v71, v71
	s_nop 0
	v_mul_f32_e32 v71, 0xbfb8aa3b, v71
	v_exp_f32_e32 v71, v71
	global_store_dword v[66:67], v71, off offset:128
.LBB0_552:
	s_or_b64 exec, exec, s[2:3]
	v_or_b32_e32 v66, v86, v74
	v_cmp_gt_i32_e32 vcc, s90, v66
	s_and_saveexec_b64 s[2:3], vcc
	s_cbranch_execz .LBB0_554
	v_lshlrev_b64 v[72:73], 2, v[64:65]
	v_lshl_add_u64 v[88:89], s[8:9], 0, v[72:73]
	v_mov_b32_e32 v67, v170
	s_mov_b32 s5, 0x3f317217
	s_mov_b32 s18, 0x7f800000
	s_mov_b32 s4, 0xc1a00000
	v_add_f32_e32 v67, v20, v67
	v_mul_f32_e32 v71, 0xbfb8aa3b, v67
	v_exp_f32_e32 v71, v71
	s_nop 0
	v_add_f32_e32 v71, 1.0, v71
	v_cmp_gt_f32_e32 vcc, s69, v71
	s_nop 1
	v_cndmask_b32_e64 v74, 0, 32, vcc
	v_ldexp_f32 v71, v71, v74
	v_log_f32_e32 v71, v71
	v_cndmask_b32_e32 v74, 0, v216, vcc
	v_mul_f32_e32 v87, 0x3f317217, v71
	v_fma_f32 v87, v71, s5, -v87
	v_fmac_f32_e32 v87, 0x3377d1cf, v71
	v_fmac_f32_e32 v87, 0x3f317217, v71
	v_cmp_lt_f32_e64 vcc, |v71|, s18
	s_nop 1
	v_cndmask_b32_e32 v71, v71, v87, vcc
	v_sub_f32_e32 v71, v71, v74
	v_cmp_gt_f32_e32 vcc, s4, v67
	s_nop 1
	v_cndmask_b32_e64 v67, v71, -v67, vcc
	v_sub_f32_e32 v67, -0.5, v67
	v_mul_f32_e32 v67, 0x3fb8aa3b, v67
	v_exp_f32_e32 v71, v67
	v_ashrrev_i32_e32 v67, 31, v66
	v_lshlrev_b64 v[66:67], 12, v[66:67]
	v_lshl_add_u64 v[66:67], s[6:7], 0, v[66:67]
	v_mul_f32_e32 v71, 0xbfb8aa3b, v71
	v_exp_f32_e32 v71, v71
	v_lshl_add_u64 v[66:67], v[66:67], 0, v[72:73]
	global_store_dword v[66:67], v71, off
	v_mov_b32_e32 v71, v171
	v_add_f32_e32 v71, v4, v71
	v_mul_f32_e32 v72, 0xbfb8aa3b, v71
	v_exp_f32_e32 v72, v72
	s_nop 0
	v_add_f32_e32 v72, 1.0, v72
	v_cmp_gt_f32_e32 vcc, s69, v72
	s_nop 1
	v_cndmask_b32_e64 v73, 0, 32, vcc
	v_ldexp_f32 v72, v72, v73
	v_log_f32_e32 v72, v72
	v_cndmask_b32_e32 v73, 0, v216, vcc
	v_mul_f32_e32 v74, 0x3f317217, v72
	v_fma_f32 v74, v72, s5, -v74
	v_fmac_f32_e32 v74, 0x3377d1cf, v72
	v_fmac_f32_e32 v74, 0x3f317217, v72
	v_cmp_lt_f32_e64 vcc, |v72|, s18
	s_nop 1
	v_cndmask_b32_e32 v72, v72, v74, vcc
	v_sub_f32_e32 v72, v72, v73
	v_cmp_gt_f32_e32 vcc, s4, v71
	s_nop 1
	v_cndmask_b32_e64 v71, v72, -v71, vcc
	v_sub_f32_e32 v71, -0.5, v71
	v_mul_f32_e32 v71, 0x3fb8aa3b, v71
	v_exp_f32_e32 v71, v71
	s_nop 0
	v_mul_f32_e32 v71, 0xbfb8aa3b, v71
	v_exp_f32_e32 v71, v71
	global_store_dword v[66:67], v71, off offset:128
